# GEMM K-loops: saddr LDS-DMA + rebalanced DMA schedule (one A-piece moved from the 6-DMA segment to the following 2-DMA segment, waits recounted)
# speedup vs baseline: 1.0025x; 1.0025x over previous
.LBB0_290:
	s_add_u32 s26, s24, 0xfffc0080
	s_addc_u32 s27, s25, -1
	s_add_u32 s52, s24, 0xfffc0000
	s_addc_u32 s53, s25, -1
	s_mov_b32 m0, s43
	ds_read_b128 v[130:133], v188
	ds_read_b128 v[134:137], v188 offset:1024
	ds_read_b128 v[138:141], v188 offset:2048
	ds_read_b128 v[154:157], v188 offset:3072
	ds_read_b128 v[158:161], v188 offset:16384
	ds_read_b128 v[162:165], v188 offset:17408
	ds_read_b128 v[166:169], v188 offset:18432
	ds_read_b128 v[176:179], v188 offset:19456
	ds_read_b128 v[180:183], v175
	ds_read_b128 v[184:187], v175 offset:1024
	ds_read_b128 v[192:195], v175 offset:2048
	ds_read_b128 v[196:199], v175 offset:3072
	ds_read_b128 v[200:203], v175 offset:4096
	ds_read_b128 v[204:207], v175 offset:5120
	ds_read_b128 v[208:211], v175 offset:6144
	ds_read_b128 v[212:215], v175 offset:7168
	global_load_lds_dwordx4 v144, s[52:53]
	s_add_i32 m0, s38, 0xc000
	s_nop 0
	global_load_lds_dwordx4 v150, s[24:25]
	s_add_i32 m0, s38, 0xe000
	s_cmp_eq_u32 s50, 12
	global_load_lds_dwordx4 v152, s[24:25]
	s_cselect_b32 s29, s17, s27
	s_cselect_b32 s28, s46, s26
	s_cselect_b32 s27, s15, s49
	s_cselect_b32 s26, s47, s48
	s_waitcnt vmcnt(8)
	s_waitcnt lgkmcnt(0)
	s_barrier
	s_setprio 1
	s_waitcnt lgkmcnt(0)
	v_mfma_f32_16x16x32_bf16 v[126:129], v[130:133], v[180:183], v[126:129]
	v_mfma_f32_16x16x32_bf16 v[122:125], v[138:141], v[180:183], v[122:125]
	v_mfma_f32_16x16x32_bf16 v[110:113], v[130:133], v[192:195], v[110:113]
	v_mfma_f32_16x16x32_bf16 v[106:109], v[138:141], v[192:195], v[106:109]
	v_mfma_f32_16x16x32_bf16 v[94:97], v[130:133], v[200:203], v[94:97]
	v_mfma_f32_16x16x32_bf16 v[90:93], v[138:141], v[200:203], v[90:93]
	v_mfma_f32_16x16x32_bf16 v[78:81], v[130:133], v[208:211], v[78:81]
	v_mfma_f32_16x16x32_bf16 v[74:77], v[138:141], v[208:211], v[74:77]
	v_mfma_f32_16x16x32_bf16 v[126:129], v[134:137], v[184:187], v[126:129]
	v_mfma_f32_16x16x32_bf16 v[122:125], v[154:157], v[184:187], v[122:125]
	v_mfma_f32_16x16x32_bf16 v[110:113], v[134:137], v[196:199], v[110:113]
	v_mfma_f32_16x16x32_bf16 v[106:109], v[154:157], v[196:199], v[106:109]
	v_mfma_f32_16x16x32_bf16 v[94:97], v[134:137], v[204:207], v[94:97]
	v_mfma_f32_16x16x32_bf16 v[90:93], v[154:157], v[204:207], v[90:93]
	v_mfma_f32_16x16x32_bf16 v[78:81], v[134:137], v[212:215], v[78:81]
	v_mfma_f32_16x16x32_bf16 v[74:77], v[154:157], v[212:215], v[74:77]
	s_setprio 0
	s_setprio 1
	v_mfma_f32_16x16x32_bf16 v[118:121], v[158:161], v[180:183], v[118:121]
	v_mfma_f32_16x16x32_bf16 v[114:117], v[166:169], v[180:183], v[114:117]
	v_mfma_f32_16x16x32_bf16 v[102:105], v[158:161], v[192:195], v[102:105]
	v_mfma_f32_16x16x32_bf16 v[98:101], v[166:169], v[192:195], v[98:101]
	v_mfma_f32_16x16x32_bf16 v[86:89], v[158:161], v[200:203], v[86:89]
	v_mfma_f32_16x16x32_bf16 v[82:85], v[166:169], v[200:203], v[82:85]
	v_mfma_f32_16x16x32_bf16 v[70:73], v[158:161], v[208:211], v[70:73]
	v_mfma_f32_16x16x32_bf16 v[66:69], v[166:169], v[208:211], v[66:69]
	v_mfma_f32_16x16x32_bf16 v[118:121], v[162:165], v[184:187], v[118:121]
	v_mfma_f32_16x16x32_bf16 v[114:117], v[176:179], v[184:187], v[114:117]
	v_mfma_f32_16x16x32_bf16 v[102:105], v[162:165], v[196:199], v[102:105]
	v_mfma_f32_16x16x32_bf16 v[98:101], v[176:179], v[196:199], v[98:101]
	v_mfma_f32_16x16x32_bf16 v[86:89], v[162:165], v[204:207], v[86:89]
	v_mfma_f32_16x16x32_bf16 v[82:85], v[176:179], v[204:207], v[82:85]
	v_mfma_f32_16x16x32_bf16 v[70:73], v[162:165], v[212:215], v[70:73]
	v_mfma_f32_16x16x32_bf16 v[66:69], v[176:179], v[212:215], v[66:69]
	s_setprio 0
	s_barrier
	s_add_i32 s51, s36, 0x10000
	s_mov_b32 m0, s51
	ds_read_b128 v[180:183], v175 offset:16384
	ds_read_b128 v[184:187], v175 offset:17408
	ds_read_b128 v[192:195], v175 offset:18432
	ds_read_b128 v[196:199], v175 offset:19456
	ds_read_b128 v[200:203], v175 offset:20480
	ds_read_b128 v[204:207], v175 offset:21504
	ds_read_b128 v[208:211], v175 offset:22528
	ds_read_b128 v[212:215], v175 offset:23552
	global_load_lds_dwordx4 v0, s[26:27]
	s_add_i32 m0, s51, 0x2000
	s_add_u32 s52, s26, 0x40000
	global_load_lds_dwordx4 v142, s[26:27]
	s_addc_u32 s53, s27, 0
	s_add_i32 s51, s36, 0x14000
	s_mov_b32 m0, s51
	s_nop 0
	global_load_lds_dwordx4 v0, s[52:53]
	s_add_i32 m0, s51, 0x2000
	s_nop 0
	global_load_lds_dwordx4 v142, s[52:53]
	s_mov_b32 m0, s38
	s_nop 0
	global_load_lds_dwordx4 v146, s[28:29]
	s_waitcnt vmcnt(7)
	s_waitcnt lgkmcnt(0)
	s_barrier
	s_setprio 1
	s_waitcnt lgkmcnt(0)
	v_mfma_f32_16x16x32_bf16 v[62:65], v[130:133], v[180:183], v[62:65]
	v_mfma_f32_16x16x32_bf16 v[58:61], v[138:141], v[180:183], v[58:61]
	v_mfma_f32_16x16x32_bf16 v[46:49], v[130:133], v[192:195], v[46:49]
	v_mfma_f32_16x16x32_bf16 v[42:45], v[138:141], v[192:195], v[42:45]
	v_mfma_f32_16x16x32_bf16 v[30:33], v[130:133], v[200:203], v[30:33]
	v_mfma_f32_16x16x32_bf16 v[26:29], v[138:141], v[200:203], v[26:29]
	v_mfma_f32_16x16x32_bf16 v[14:17], v[130:133], v[208:211], v[14:17]
	v_mfma_f32_16x16x32_bf16 v[10:13], v[138:141], v[208:211], v[10:13]
	v_mfma_f32_16x16x32_bf16 v[62:65], v[134:137], v[184:187], v[62:65]
	v_mfma_f32_16x16x32_bf16 v[58:61], v[154:157], v[184:187], v[58:61]
	v_mfma_f32_16x16x32_bf16 v[46:49], v[134:137], v[196:199], v[46:49]
	v_mfma_f32_16x16x32_bf16 v[42:45], v[154:157], v[196:199], v[42:45]
	v_mfma_f32_16x16x32_bf16 v[30:33], v[134:137], v[204:207], v[30:33]
	v_mfma_f32_16x16x32_bf16 v[26:29], v[154:157], v[204:207], v[26:29]
	v_mfma_f32_16x16x32_bf16 v[14:17], v[134:137], v[212:215], v[14:17]
	v_mfma_f32_16x16x32_bf16 v[10:13], v[154:157], v[212:215], v[10:13]
	s_setprio 0
	s_setprio 1
	v_mfma_f32_16x16x32_bf16 v[54:57], v[158:161], v[180:183], v[54:57]
	v_mfma_f32_16x16x32_bf16 v[50:53], v[166:169], v[180:183], v[50:53]
	v_mfma_f32_16x16x32_bf16 v[38:41], v[158:161], v[192:195], v[38:41]
	v_mfma_f32_16x16x32_bf16 v[34:37], v[166:169], v[192:195], v[34:37]
	v_mfma_f32_16x16x32_bf16 v[22:25], v[158:161], v[200:203], v[22:25]
	v_mfma_f32_16x16x32_bf16 v[18:21], v[166:169], v[200:203], v[18:21]
	v_mfma_f32_16x16x32_bf16 v[6:9], v[158:161], v[208:211], v[6:9]
	v_mfma_f32_16x16x32_bf16 v[2:5], v[166:169], v[208:211], v[2:5]
	v_mfma_f32_16x16x32_bf16 v[54:57], v[162:165], v[184:187], v[54:57]
	v_mfma_f32_16x16x32_bf16 v[50:53], v[176:179], v[184:187], v[50:53]
	v_mfma_f32_16x16x32_bf16 v[38:41], v[162:165], v[196:199], v[38:41]
	v_mfma_f32_16x16x32_bf16 v[34:37], v[176:179], v[196:199], v[34:37]
	v_mfma_f32_16x16x32_bf16 v[22:25], v[162:165], v[204:207], v[22:25]
	v_mfma_f32_16x16x32_bf16 v[18:21], v[176:179], v[204:207], v[18:21]
	v_mfma_f32_16x16x32_bf16 v[6:9], v[162:165], v[212:215], v[6:9]
	v_mfma_f32_16x16x32_bf16 v[2:5], v[176:179], v[212:215], v[2:5]
	s_setprio 0
	s_barrier
	s_mov_b32 m0, s39
	ds_read_b128 v[130:133], v188 offset:32768
	ds_read_b128 v[134:137], v188 offset:33792
	ds_read_b128 v[138:141], v188 offset:34816
	ds_read_b128 v[154:157], v188 offset:35840
	ds_read_b128 v[158:161], v188 offset:49152
	ds_read_b128 v[162:165], v188 offset:50176
	ds_read_b128 v[166:169], v188 offset:51200
	ds_read_b128 v[176:179], v188 offset:52224
	ds_read_b128 v[180:183], v175 offset:32768
	ds_read_b128 v[184:187], v175 offset:33792
	ds_read_b128 v[192:195], v175 offset:34816
	ds_read_b128 v[196:199], v175 offset:35840
	ds_read_b128 v[200:203], v175 offset:36864
	ds_read_b128 v[204:207], v175 offset:37888
	ds_read_b128 v[208:211], v175 offset:38912
	ds_read_b128 v[212:215], v175 offset:39936
	global_load_lds_dwordx4 v144, s[28:29]
	s_add_u32 s28, s28, 0x40000
	s_addc_u32 s29, s29, 0
	s_mov_b32 m0, s40
	s_nop 0
	global_load_lds_dwordx4 v146, s[28:29]
	s_mov_b32 m0, s41
	s_nop 0
	global_load_lds_dwordx4 v144, s[28:29]
	s_waitcnt vmcnt(8)
	s_waitcnt lgkmcnt(0)
	s_barrier
	s_setprio 1
	s_waitcnt lgkmcnt(0)
	v_mfma_f32_16x16x32_bf16 v[126:129], v[130:133], v[180:183], v[126:129]
	v_mfma_f32_16x16x32_bf16 v[122:125], v[138:141], v[180:183], v[122:125]
	v_mfma_f32_16x16x32_bf16 v[110:113], v[130:133], v[192:195], v[110:113]
	v_mfma_f32_16x16x32_bf16 v[106:109], v[138:141], v[192:195], v[106:109]
	v_mfma_f32_16x16x32_bf16 v[94:97], v[130:133], v[200:203], v[94:97]
	v_mfma_f32_16x16x32_bf16 v[90:93], v[138:141], v[200:203], v[90:93]
	v_mfma_f32_16x16x32_bf16 v[78:81], v[130:133], v[208:211], v[78:81]
	v_mfma_f32_16x16x32_bf16 v[74:77], v[138:141], v[208:211], v[74:77]
	v_mfma_f32_16x16x32_bf16 v[126:129], v[134:137], v[184:187], v[126:129]
	v_mfma_f32_16x16x32_bf16 v[122:125], v[154:157], v[184:187], v[122:125]
	v_mfma_f32_16x16x32_bf16 v[110:113], v[134:137], v[196:199], v[110:113]
	v_mfma_f32_16x16x32_bf16 v[106:109], v[154:157], v[196:199], v[106:109]
	v_mfma_f32_16x16x32_bf16 v[94:97], v[134:137], v[204:207], v[94:97]
	v_mfma_f32_16x16x32_bf16 v[90:93], v[154:157], v[204:207], v[90:93]
	v_mfma_f32_16x16x32_bf16 v[78:81], v[134:137], v[212:215], v[78:81]
	v_mfma_f32_16x16x32_bf16 v[74:77], v[154:157], v[212:215], v[74:77]
	s_setprio 0
	s_setprio 1
	v_mfma_f32_16x16x32_bf16 v[118:121], v[158:161], v[180:183], v[118:121]
	v_mfma_f32_16x16x32_bf16 v[114:117], v[166:169], v[180:183], v[114:117]
	v_mfma_f32_16x16x32_bf16 v[102:105], v[158:161], v[192:195], v[102:105]
	v_mfma_f32_16x16x32_bf16 v[98:101], v[166:169], v[192:195], v[98:101]
	v_mfma_f32_16x16x32_bf16 v[86:89], v[158:161], v[200:203], v[86:89]
	v_mfma_f32_16x16x32_bf16 v[82:85], v[166:169], v[200:203], v[82:85]
	v_mfma_f32_16x16x32_bf16 v[70:73], v[158:161], v[208:211], v[70:73]
	v_mfma_f32_16x16x32_bf16 v[66:69], v[166:169], v[208:211], v[66:69]
	v_mfma_f32_16x16x32_bf16 v[118:121], v[162:165], v[184:187], v[118:121]
	v_mfma_f32_16x16x32_bf16 v[114:117], v[176:179], v[184:187], v[114:117]
	v_mfma_f32_16x16x32_bf16 v[102:105], v[162:165], v[196:199], v[102:105]
	v_mfma_f32_16x16x32_bf16 v[98:101], v[176:179], v[196:199], v[98:101]
	v_mfma_f32_16x16x32_bf16 v[86:89], v[162:165], v[204:207], v[86:89]
	v_mfma_f32_16x16x32_bf16 v[82:85], v[176:179], v[204:207], v[82:85]
	v_mfma_f32_16x16x32_bf16 v[70:73], v[162:165], v[212:215], v[70:73]
	v_mfma_f32_16x16x32_bf16 v[66:69], v[176:179], v[212:215], v[66:69]
	s_setprio 0
	s_barrier
	s_add_u32 s26, s26, 0x80
	s_addc_u32 s27, s27, 0
	s_add_i32 s51, s36, 0x18000
	s_mov_b32 m0, s51
	ds_read_b128 v[180:183], v175 offset:49152
	ds_read_b128 v[184:187], v175 offset:50176
	ds_read_b128 v[192:195], v175 offset:51200
	ds_read_b128 v[196:199], v175 offset:52224
	ds_read_b128 v[200:203], v175 offset:53248
	ds_read_b128 v[204:207], v175 offset:54272
	ds_read_b128 v[208:211], v175 offset:55296
	ds_read_b128 v[212:215], v175 offset:56320
	global_load_lds_dwordx4 v0, s[26:27]
	s_add_i32 m0, s51, 0x2000
	s_add_u32 s52, s26, 0x40000
	global_load_lds_dwordx4 v142, s[26:27]
	s_addc_u32 s53, s27, 0
	s_add_i32 s51, s36, 0x1c000
	s_mov_b32 m0, s51
	s_add_u32 s28, s28, 0xfffc0080
	global_load_lds_dwordx4 v0, s[52:53]
	s_addc_u32 s29, s29, -1
	s_add_i32 m0, s51, 0x2000
	s_nop 0
	global_load_lds_dwordx4 v142, s[52:53]
	s_mov_b32 m0, s42
	s_nop 0
	global_load_lds_dwordx4 v146, s[28:29]
	s_waitcnt vmcnt(7)
	s_waitcnt lgkmcnt(0)
	s_barrier
	s_setprio 1
	s_waitcnt lgkmcnt(0)
	v_mfma_f32_16x16x32_bf16 v[62:65], v[130:133], v[180:183], v[62:65]
	v_mfma_f32_16x16x32_bf16 v[58:61], v[138:141], v[180:183], v[58:61]
	v_mfma_f32_16x16x32_bf16 v[46:49], v[130:133], v[192:195], v[46:49]
	v_mfma_f32_16x16x32_bf16 v[42:45], v[138:141], v[192:195], v[42:45]
	v_mfma_f32_16x16x32_bf16 v[30:33], v[130:133], v[200:203], v[30:33]
	v_mfma_f32_16x16x32_bf16 v[26:29], v[138:141], v[200:203], v[26:29]
	v_mfma_f32_16x16x32_bf16 v[14:17], v[130:133], v[208:211], v[14:17]
	v_mfma_f32_16x16x32_bf16 v[10:13], v[138:141], v[208:211], v[10:13]
	v_mfma_f32_16x16x32_bf16 v[62:65], v[134:137], v[184:187], v[62:65]
	v_mfma_f32_16x16x32_bf16 v[58:61], v[154:157], v[184:187], v[58:61]
	v_mfma_f32_16x16x32_bf16 v[46:49], v[134:137], v[196:199], v[46:49]
	v_mfma_f32_16x16x32_bf16 v[42:45], v[154:157], v[196:199], v[42:45]
	v_mfma_f32_16x16x32_bf16 v[30:33], v[134:137], v[204:207], v[30:33]
	v_mfma_f32_16x16x32_bf16 v[26:29], v[154:157], v[204:207], v[26:29]
	v_mfma_f32_16x16x32_bf16 v[14:17], v[134:137], v[212:215], v[14:17]
	v_mfma_f32_16x16x32_bf16 v[10:13], v[154:157], v[212:215], v[10:13]
	s_setprio 0
	s_setprio 1
	v_mfma_f32_16x16x32_bf16 v[54:57], v[158:161], v[180:183], v[54:57]
	v_mfma_f32_16x16x32_bf16 v[50:53], v[166:169], v[180:183], v[50:53]
	v_mfma_f32_16x16x32_bf16 v[38:41], v[158:161], v[192:195], v[38:41]
	v_mfma_f32_16x16x32_bf16 v[34:37], v[166:169], v[192:195], v[34:37]
	v_mfma_f32_16x16x32_bf16 v[22:25], v[158:161], v[200:203], v[22:25]
	v_mfma_f32_16x16x32_bf16 v[18:21], v[166:169], v[200:203], v[18:21]
	v_mfma_f32_16x16x32_bf16 v[6:9], v[158:161], v[208:211], v[6:9]
	v_mfma_f32_16x16x32_bf16 v[2:5], v[166:169], v[208:211], v[2:5]
	v_mfma_f32_16x16x32_bf16 v[54:57], v[162:165], v[184:187], v[54:57]
	v_mfma_f32_16x16x32_bf16 v[50:53], v[176:179], v[184:187], v[50:53]
	v_mfma_f32_16x16x32_bf16 v[38:41], v[162:165], v[196:199], v[38:41]
	v_mfma_f32_16x16x32_bf16 v[34:37], v[176:179], v[196:199], v[34:37]
	v_mfma_f32_16x16x32_bf16 v[22:25], v[162:165], v[204:207], v[22:25]
	v_mfma_f32_16x16x32_bf16 v[18:21], v[176:179], v[204:207], v[18:21]
	v_mfma_f32_16x16x32_bf16 v[6:9], v[162:165], v[212:215], v[6:9]
	v_mfma_f32_16x16x32_bf16 v[2:5], v[176:179], v[212:215], v[2:5]
	s_setprio 0
	s_barrier
	s_add_i32 s50, s50, 2
	s_add_u32 s24, s24, 0x100
	s_addc_u32 s25, s25, 0
	s_add_u32 s48, s48, 0x100
	s_addc_u32 s49, s49, 0
	s_cmp_gt_u32 s50, 13
	s_cbranch_scc0 .LBB0_290
	s_and_b64 vcc, exec, s[12:13]
	s_cbranch_vccz .LBB0_293
	s_barrier

.LBB0_331:
	s_add_i32 s68, s34, 2
	s_add_u32 s69, s30, 0x80
	s_addc_u32 s35, s31, 0
	s_mov_b32 m0, s50
	ds_read_b128 v[130:133], v210
	ds_read_b128 v[134:137], v210 offset:1024
	ds_read_b128 v[138:141], v210 offset:2048
	ds_read_b128 v[142:145], v210 offset:3072
	ds_read_b128 v[146:149], v210 offset:16384
	ds_read_b128 v[150:153], v210 offset:17408
	ds_read_b128 v[154:157], v210 offset:18432
	ds_read_b128 v[158:161], v210 offset:19456
	ds_read_b128 v[162:165], v247
	ds_read_b128 v[166:169], v247 offset:1024
	ds_read_b128 v[170:173], v247 offset:2048
	ds_read_b128 v[174:177], v247 offset:3072
	ds_read_b128 v[178:181], v247 offset:4096
	ds_read_b128 v[182:185], v247 offset:5120
	ds_read_b128 v[202:205], v247 offset:6144
	ds_read_b128 v[206:209], v247 offset:7168
	global_load_lds_dwordx4 v188, s[30:31]
	s_add_i32 m0, s43, 0xc000
	s_nop 0
	global_load_lds_dwordx4 v198, s[30:31]
	s_add_i32 m0, s43, 0xe000
	s_cmp_eq_u32 s51, s34
	global_load_lds_dwordx4 v200, s[30:31]
	s_cselect_b32 s35, s11, s35
	s_cselect_b32 s34, s10, s69
	s_cselect_b32 s71, s13, s67
	s_cselect_b32 s70, s12, s66
	s_waitcnt vmcnt(8)
	s_waitcnt lgkmcnt(0)
	s_barrier
	s_setprio 1
	s_waitcnt lgkmcnt(0)
	v_mfma_f32_16x16x32_bf16 v[126:129], v[130:133], v[162:165], v[126:129]
	v_mfma_f32_16x16x32_bf16 v[122:125], v[138:141], v[162:165], v[122:125]
	v_mfma_f32_16x16x32_bf16 v[110:113], v[130:133], v[170:173], v[110:113]
	v_mfma_f32_16x16x32_bf16 v[106:109], v[138:141], v[170:173], v[106:109]
	v_mfma_f32_16x16x32_bf16 v[94:97], v[130:133], v[178:181], v[94:97]
	v_mfma_f32_16x16x32_bf16 v[90:93], v[138:141], v[178:181], v[90:93]
	v_mfma_f32_16x16x32_bf16 v[78:81], v[130:133], v[202:205], v[78:81]
	v_mfma_f32_16x16x32_bf16 v[74:77], v[138:141], v[202:205], v[74:77]
	v_mfma_f32_16x16x32_bf16 v[126:129], v[134:137], v[166:169], v[126:129]
	v_mfma_f32_16x16x32_bf16 v[122:125], v[142:145], v[166:169], v[122:125]
	v_mfma_f32_16x16x32_bf16 v[110:113], v[134:137], v[174:177], v[110:113]
	v_mfma_f32_16x16x32_bf16 v[106:109], v[142:145], v[174:177], v[106:109]
	v_mfma_f32_16x16x32_bf16 v[94:97], v[134:137], v[182:185], v[94:97]
	v_mfma_f32_16x16x32_bf16 v[90:93], v[142:145], v[182:185], v[90:93]
	v_mfma_f32_16x16x32_bf16 v[78:81], v[134:137], v[206:209], v[78:81]
	v_mfma_f32_16x16x32_bf16 v[74:77], v[142:145], v[206:209], v[74:77]
	s_setprio 0
	s_setprio 1
	v_mfma_f32_16x16x32_bf16 v[118:121], v[146:149], v[162:165], v[118:121]
	v_mfma_f32_16x16x32_bf16 v[114:117], v[154:157], v[162:165], v[114:117]
	v_mfma_f32_16x16x32_bf16 v[102:105], v[146:149], v[170:173], v[102:105]
	v_mfma_f32_16x16x32_bf16 v[98:101], v[154:157], v[170:173], v[98:101]
	v_mfma_f32_16x16x32_bf16 v[86:89], v[146:149], v[178:181], v[86:89]
	v_mfma_f32_16x16x32_bf16 v[82:85], v[154:157], v[178:181], v[82:85]
	v_mfma_f32_16x16x32_bf16 v[70:73], v[146:149], v[202:205], v[70:73]
	v_mfma_f32_16x16x32_bf16 v[66:69], v[154:157], v[202:205], v[66:69]
	v_mfma_f32_16x16x32_bf16 v[118:121], v[150:153], v[166:169], v[118:121]
	v_mfma_f32_16x16x32_bf16 v[114:117], v[158:161], v[166:169], v[114:117]
	v_mfma_f32_16x16x32_bf16 v[102:105], v[150:153], v[174:177], v[102:105]
	v_mfma_f32_16x16x32_bf16 v[98:101], v[158:161], v[174:177], v[98:101]
	v_mfma_f32_16x16x32_bf16 v[86:89], v[150:153], v[182:185], v[86:89]
	v_mfma_f32_16x16x32_bf16 v[82:85], v[158:161], v[182:185], v[82:85]
	v_mfma_f32_16x16x32_bf16 v[70:73], v[150:153], v[206:209], v[70:73]
	v_mfma_f32_16x16x32_bf16 v[66:69], v[158:161], v[206:209], v[66:69]
	s_setprio 0
	s_barrier
	s_add_i32 s72, s38, 0x10000
	s_mov_b32 m0, s72
	ds_read_b128 v[162:165], v247 offset:16384
	ds_read_b128 v[166:169], v247 offset:17408
	ds_read_b128 v[170:173], v247 offset:18432
	ds_read_b128 v[174:177], v247 offset:19456
	ds_read_b128 v[178:181], v247 offset:20480
	ds_read_b128 v[182:185], v247 offset:21504
	ds_read_b128 v[202:205], v247 offset:22528
	ds_read_b128 v[206:209], v247 offset:23552
	global_load_lds_dwordx4 v0, s[70:71]
	s_add_i32 m0, s72, 0x2000
	s_add_i32 s72, s38, 0x14000
	global_load_lds_dwordx4 v192, s[70:71]
	s_add_u32 s70, s70, s22
	s_addc_u32 s71, s71, 0
	s_mov_b32 m0, s72
	s_nop 0
	global_load_lds_dwordx4 v0, s[70:71]
	s_add_i32 m0, s72, 0x2000
	s_nop 0
	global_load_lds_dwordx4 v192, s[70:71]
	s_mov_b32 m0, s43
	s_nop 0
	global_load_lds_dwordx4 v186, s[34:35]
	s_waitcnt vmcnt(7)
	s_waitcnt lgkmcnt(0)
	s_barrier
	s_setprio 1
	s_waitcnt lgkmcnt(0)
	v_mfma_f32_16x16x32_bf16 v[62:65], v[130:133], v[162:165], v[62:65]
	v_mfma_f32_16x16x32_bf16 v[58:61], v[138:141], v[162:165], v[58:61]
	v_mfma_f32_16x16x32_bf16 v[46:49], v[130:133], v[170:173], v[46:49]
	v_mfma_f32_16x16x32_bf16 v[42:45], v[138:141], v[170:173], v[42:45]
	v_mfma_f32_16x16x32_bf16 v[30:33], v[130:133], v[178:181], v[30:33]
	v_mfma_f32_16x16x32_bf16 v[26:29], v[138:141], v[178:181], v[26:29]
	v_mfma_f32_16x16x32_bf16 v[14:17], v[130:133], v[202:205], v[14:17]
	v_mfma_f32_16x16x32_bf16 v[10:13], v[138:141], v[202:205], v[10:13]
	v_mfma_f32_16x16x32_bf16 v[62:65], v[134:137], v[166:169], v[62:65]
	v_mfma_f32_16x16x32_bf16 v[58:61], v[142:145], v[166:169], v[58:61]
	v_mfma_f32_16x16x32_bf16 v[46:49], v[134:137], v[174:177], v[46:49]
	v_mfma_f32_16x16x32_bf16 v[42:45], v[142:145], v[174:177], v[42:45]
	v_mfma_f32_16x16x32_bf16 v[30:33], v[134:137], v[182:185], v[30:33]
	v_mfma_f32_16x16x32_bf16 v[26:29], v[142:145], v[182:185], v[26:29]
	v_mfma_f32_16x16x32_bf16 v[14:17], v[134:137], v[206:209], v[14:17]
	v_mfma_f32_16x16x32_bf16 v[10:13], v[142:145], v[206:209], v[10:13]
	s_setprio 0
	s_setprio 1
	v_mfma_f32_16x16x32_bf16 v[54:57], v[146:149], v[162:165], v[54:57]
	v_mfma_f32_16x16x32_bf16 v[50:53], v[154:157], v[162:165], v[50:53]
	v_mfma_f32_16x16x32_bf16 v[38:41], v[146:149], v[170:173], v[38:41]
	v_mfma_f32_16x16x32_bf16 v[34:37], v[154:157], v[170:173], v[34:37]
	v_mfma_f32_16x16x32_bf16 v[22:25], v[146:149], v[178:181], v[22:25]
	v_mfma_f32_16x16x32_bf16 v[18:21], v[154:157], v[178:181], v[18:21]
	v_mfma_f32_16x16x32_bf16 v[6:9], v[146:149], v[202:205], v[6:9]
	v_mfma_f32_16x16x32_bf16 v[2:5], v[154:157], v[202:205], v[2:5]
	v_mfma_f32_16x16x32_bf16 v[54:57], v[150:153], v[166:169], v[54:57]
	v_mfma_f32_16x16x32_bf16 v[50:53], v[158:161], v[166:169], v[50:53]
	v_mfma_f32_16x16x32_bf16 v[38:41], v[150:153], v[174:177], v[38:41]
	v_mfma_f32_16x16x32_bf16 v[34:37], v[158:161], v[174:177], v[34:37]
	v_mfma_f32_16x16x32_bf16 v[22:25], v[150:153], v[182:185], v[22:25]
	v_mfma_f32_16x16x32_bf16 v[18:21], v[158:161], v[182:185], v[18:21]
	v_mfma_f32_16x16x32_bf16 v[6:9], v[150:153], v[206:209], v[6:9]
	v_mfma_f32_16x16x32_bf16 v[2:5], v[158:161], v[206:209], v[2:5]
	s_setprio 0
	s_barrier
	s_mov_b32 m0, s44
	ds_read_b128 v[130:133], v210 offset:32768
	ds_read_b128 v[134:137], v210 offset:33792
	ds_read_b128 v[138:141], v210 offset:34816
	ds_read_b128 v[142:145], v210 offset:35840
	ds_read_b128 v[146:149], v210 offset:49152
	ds_read_b128 v[150:153], v210 offset:50176
	ds_read_b128 v[154:157], v210 offset:51200
	ds_read_b128 v[158:161], v210 offset:52224
	ds_read_b128 v[162:165], v247 offset:32768
	ds_read_b128 v[166:169], v247 offset:33792
	ds_read_b128 v[170:173], v247 offset:34816
	ds_read_b128 v[174:177], v247 offset:35840
	ds_read_b128 v[178:181], v247 offset:36864
	ds_read_b128 v[182:185], v247 offset:37888
	ds_read_b128 v[202:205], v247 offset:38912
	ds_read_b128 v[206:209], v247 offset:39936
	global_load_lds_dwordx4 v188, s[34:35]
	s_add_u32 s34, s34, s22
	s_addc_u32 s35, s35, 0
	s_mov_b32 m0, s45
	s_nop 0
	global_load_lds_dwordx4 v186, s[34:35]
	s_mov_b32 m0, s46
	s_nop 0
	global_load_lds_dwordx4 v188, s[34:35]
	s_waitcnt vmcnt(8)
	s_waitcnt lgkmcnt(0)
	s_barrier
	s_setprio 1
	s_waitcnt lgkmcnt(0)
	v_mfma_f32_16x16x32_bf16 v[126:129], v[130:133], v[162:165], v[126:129]
	v_mfma_f32_16x16x32_bf16 v[122:125], v[138:141], v[162:165], v[122:125]
	v_mfma_f32_16x16x32_bf16 v[110:113], v[130:133], v[170:173], v[110:113]
	v_mfma_f32_16x16x32_bf16 v[106:109], v[138:141], v[170:173], v[106:109]
	v_mfma_f32_16x16x32_bf16 v[94:97], v[130:133], v[178:181], v[94:97]
	v_mfma_f32_16x16x32_bf16 v[90:93], v[138:141], v[178:181], v[90:93]
	v_mfma_f32_16x16x32_bf16 v[78:81], v[130:133], v[202:205], v[78:81]
	v_mfma_f32_16x16x32_bf16 v[74:77], v[138:141], v[202:205], v[74:77]
	v_mfma_f32_16x16x32_bf16 v[126:129], v[134:137], v[166:169], v[126:129]
	v_mfma_f32_16x16x32_bf16 v[122:125], v[142:145], v[166:169], v[122:125]
	v_mfma_f32_16x16x32_bf16 v[110:113], v[134:137], v[174:177], v[110:113]
	v_mfma_f32_16x16x32_bf16 v[106:109], v[142:145], v[174:177], v[106:109]
	v_mfma_f32_16x16x32_bf16 v[94:97], v[134:137], v[182:185], v[94:97]
	v_mfma_f32_16x16x32_bf16 v[90:93], v[142:145], v[182:185], v[90:93]
	v_mfma_f32_16x16x32_bf16 v[78:81], v[134:137], v[206:209], v[78:81]
	v_mfma_f32_16x16x32_bf16 v[74:77], v[142:145], v[206:209], v[74:77]
	s_setprio 0
	s_setprio 1
	v_mfma_f32_16x16x32_bf16 v[118:121], v[146:149], v[162:165], v[118:121]
	v_mfma_f32_16x16x32_bf16 v[114:117], v[154:157], v[162:165], v[114:117]
	v_mfma_f32_16x16x32_bf16 v[102:105], v[146:149], v[170:173], v[102:105]
	v_mfma_f32_16x16x32_bf16 v[98:101], v[154:157], v[170:173], v[98:101]
	v_mfma_f32_16x16x32_bf16 v[86:89], v[146:149], v[178:181], v[86:89]
	v_mfma_f32_16x16x32_bf16 v[82:85], v[154:157], v[178:181], v[82:85]
	v_mfma_f32_16x16x32_bf16 v[70:73], v[146:149], v[202:205], v[70:73]
	v_mfma_f32_16x16x32_bf16 v[66:69], v[154:157], v[202:205], v[66:69]
	v_mfma_f32_16x16x32_bf16 v[118:121], v[150:153], v[166:169], v[118:121]
	v_mfma_f32_16x16x32_bf16 v[114:117], v[158:161], v[166:169], v[114:117]
	v_mfma_f32_16x16x32_bf16 v[102:105], v[150:153], v[174:177], v[102:105]
	v_mfma_f32_16x16x32_bf16 v[98:101], v[158:161], v[174:177], v[98:101]
	v_mfma_f32_16x16x32_bf16 v[86:89], v[150:153], v[182:185], v[86:89]
	v_mfma_f32_16x16x32_bf16 v[82:85], v[158:161], v[182:185], v[82:85]
	v_mfma_f32_16x16x32_bf16 v[70:73], v[150:153], v[206:209], v[70:73]
	v_mfma_f32_16x16x32_bf16 v[66:69], v[158:161], v[206:209], v[66:69]
	s_setprio 0
	s_barrier
	s_add_u32 s70, s70, 0x80
	s_addc_u32 s71, s71, 0
	s_add_i32 s72, s38, 0x1c000
	s_mov_b32 m0, s72
	ds_read_b128 v[162:165], v247 offset:49152
	ds_read_b128 v[166:169], v247 offset:50176
	ds_read_b128 v[170:173], v247 offset:51200
	ds_read_b128 v[174:177], v247 offset:52224
	ds_read_b128 v[178:181], v247 offset:53248
	ds_read_b128 v[182:185], v247 offset:54272
	ds_read_b128 v[202:205], v247 offset:55296
	ds_read_b128 v[206:209], v247 offset:56320
	global_load_lds_dwordx4 v0, s[70:71]
	s_add_i32 m0, s72, 0x2000
	s_add_i32 s72, s38, 0x18000
	global_load_lds_dwordx4 v192, s[70:71]
	s_sub_u32 s70, s70, s22
	s_subb_u32 s71, s71, 0
	s_mov_b32 m0, s72
	s_sub_u32 s34, s34, s22
	global_load_lds_dwordx4 v0, s[70:71]
	s_subb_u32 s35, s35, 0
	s_add_i32 m0, s72, 0x2000
	s_add_u32 s34, s34, 0x80
	global_load_lds_dwordx4 v192, s[70:71]
	s_addc_u32 s35, s35, 0
	s_mov_b32 m0, s49
	s_nop 0
	global_load_lds_dwordx4 v186, s[34:35]
	s_waitcnt vmcnt(7)
	s_waitcnt lgkmcnt(0)
	s_barrier
	s_setprio 1
	s_waitcnt lgkmcnt(0)
	v_mfma_f32_16x16x32_bf16 v[62:65], v[130:133], v[162:165], v[62:65]
	v_mfma_f32_16x16x32_bf16 v[58:61], v[138:141], v[162:165], v[58:61]
	v_mfma_f32_16x16x32_bf16 v[46:49], v[130:133], v[170:173], v[46:49]
	v_mfma_f32_16x16x32_bf16 v[42:45], v[138:141], v[170:173], v[42:45]
	v_mfma_f32_16x16x32_bf16 v[30:33], v[130:133], v[178:181], v[30:33]
	v_mfma_f32_16x16x32_bf16 v[26:29], v[138:141], v[178:181], v[26:29]
	v_mfma_f32_16x16x32_bf16 v[14:17], v[130:133], v[202:205], v[14:17]
	v_mfma_f32_16x16x32_bf16 v[10:13], v[138:141], v[202:205], v[10:13]
	v_mfma_f32_16x16x32_bf16 v[62:65], v[134:137], v[166:169], v[62:65]
	v_mfma_f32_16x16x32_bf16 v[58:61], v[142:145], v[166:169], v[58:61]
	v_mfma_f32_16x16x32_bf16 v[46:49], v[134:137], v[174:177], v[46:49]
	v_mfma_f32_16x16x32_bf16 v[42:45], v[142:145], v[174:177], v[42:45]
	v_mfma_f32_16x16x32_bf16 v[30:33], v[134:137], v[182:185], v[30:33]
	v_mfma_f32_16x16x32_bf16 v[26:29], v[142:145], v[182:185], v[26:29]
	v_mfma_f32_16x16x32_bf16 v[14:17], v[134:137], v[206:209], v[14:17]
	v_mfma_f32_16x16x32_bf16 v[10:13], v[142:145], v[206:209], v[10:13]
	s_setprio 0
	s_setprio 1
	v_mfma_f32_16x16x32_bf16 v[54:57], v[146:149], v[162:165], v[54:57]
	v_mfma_f32_16x16x32_bf16 v[50:53], v[154:157], v[162:165], v[50:53]
	v_mfma_f32_16x16x32_bf16 v[38:41], v[146:149], v[170:173], v[38:41]
	v_mfma_f32_16x16x32_bf16 v[34:37], v[154:157], v[170:173], v[34:37]
	v_mfma_f32_16x16x32_bf16 v[22:25], v[146:149], v[178:181], v[22:25]
	v_mfma_f32_16x16x32_bf16 v[18:21], v[154:157], v[178:181], v[18:21]
	v_mfma_f32_16x16x32_bf16 v[6:9], v[146:149], v[202:205], v[6:9]
	v_mfma_f32_16x16x32_bf16 v[2:5], v[154:157], v[202:205], v[2:5]
	v_mfma_f32_16x16x32_bf16 v[54:57], v[150:153], v[166:169], v[54:57]
	v_mfma_f32_16x16x32_bf16 v[50:53], v[158:161], v[166:169], v[50:53]
	v_mfma_f32_16x16x32_bf16 v[38:41], v[150:153], v[174:177], v[38:41]
	v_mfma_f32_16x16x32_bf16 v[34:37], v[158:161], v[174:177], v[34:37]
	v_mfma_f32_16x16x32_bf16 v[22:25], v[150:153], v[182:185], v[22:25]
	v_mfma_f32_16x16x32_bf16 v[18:21], v[158:161], v[182:185], v[18:21]
	v_mfma_f32_16x16x32_bf16 v[6:9], v[150:153], v[206:209], v[6:9]
	v_mfma_f32_16x16x32_bf16 v[2:5], v[158:161], v[206:209], v[2:5]
	s_setprio 0
	s_barrier
	s_add_u32 s30, s30, 0x100
	s_addc_u32 s31, s31, 0
	s_add_u32 s66, s66, 0x100
	s_addc_u32 s67, s67, 0
	s_cmp_ge_u32 s68, s48
	s_mov_b32 s34, s68
	s_cbranch_scc0 .LBB0_331
	v_lshl_add_u32 v204, s65, 8, v191
	v_lshl_or_b32 v202, s64, 8, v246
	v_or_b32_e32 v210, 16, v204
	v_or_b32_e32 v208, 32, v204
	v_or_b32_e32 v206, 48, v204
	s_andn2_b64 vcc, exec, s[28:29]
	v_ashrrev_i32_e32 v203, 31, v202
	v_ashrrev_i32_e32 v205, 31, v204
	v_ashrrev_i32_e32 v211, 31, v210
	v_ashrrev_i32_e32 v209, 31, v208
	v_ashrrev_i32_e32 v207, 31, v206
	s_cbranch_vccnz .LBB0_350
	s_cmp_lt_i32 s65, 64
	s_cselect_b32 s30, s19, s17
	s_cselect_b32 s31, s18, s16
	v_mov_b32_e32 v130, s31
	v_mov_b32_e32 v131, s30
	v_lshl_add_u64 v[212:213], v[202:203], 2, v[130:131]
	v_lshlrev_b64 v[130:131], 12, v[204:205]
	v_lshl_add_u64 v[130:131], v[212:213], 0, v[130:131]
	global_load_dwordx4 v[182:185], v[130:131], off offset:16 nt
	global_load_dwordx4 v[214:217], v[130:131], off nt
	global_load_dwordx4 v[178:181], v[130:131], off offset:528 nt
	global_load_dwordx4 v[218:221], v[130:131], off offset:512 nt
	v_lshlrev_b64 v[130:131], 12, v[210:211]
	v_lshl_add_u64 v[130:131], v[212:213], 0, v[130:131]
	global_load_dwordx4 v[170:173], v[130:131], off offset:16 nt
	global_load_dwordx4 v[174:177], v[130:131], off nt
	global_load_dwordx4 v[162:165], v[130:131], off offset:528 nt
	global_load_dwordx4 v[166:169], v[130:131], off offset:512 nt
	v_lshlrev_b64 v[130:131], 12, v[208:209]
	v_lshl_add_u64 v[130:131], v[212:213], 0, v[130:131]
	global_load_dwordx4 v[154:157], v[130:131], off offset:16 nt
	global_load_dwordx4 v[158:161], v[130:131], off nt
	global_load_dwordx4 v[138:141], v[130:131], off offset:528 nt
	global_load_dwordx4 v[146:149], v[130:131], off offset:512 nt
	v_lshlrev_b64 v[130:131], 12, v[206:207]
	v_lshl_add_u64 v[134:135], v[212:213], 0, v[130:131]
	global_load_dwordx4 v[142:145], v[134:135], off offset:16 nt
	global_load_dwordx4 v[150:153], v[134:135], off nt
	global_load_dwordx4 v[130:133], v[134:135], off offset:528 nt
	s_nop 0
	global_load_dwordx4 v[134:137], v[134:135], off offset:512 nt
	v_cmp_lt_i32_e32 vcc, v239, v244
	v_lshlrev_b64 v[224:225], 11, v[204:205]
	s_lshl_b32 s30, s64, 2
	v_cndmask_b32_e32 v195, v234, v239, vcc
	v_cmp_lt_i32_e32 vcc, v240, v244
	v_lshlrev_b32_e32 v248, 2, v195
	s_ashr_i32 s31, s30, 31
	v_cndmask_b32_e32 v195, v234, v240, vcc
	v_lshlrev_b32_e32 v249, 2, v195
	v_mov_b32_e32 v195, v194
	s_waitcnt vmcnt(0)
	v_pk_fma_f32 v[226:227], v[194:195], v[124:125], v[184:185]
	v_pk_fma_f32 v[184:185], v[196:197], v[122:123], v[182:183]
	v_pk_fma_f32 v[216:217], v[194:195], v[128:129], v[216:217]
	v_pk_fma_f32 v[214:215], v[196:197], v[126:127], v[214:215]
	v_pk_mul_f32 v[182:183], v[226:227], v[226:227]
	v_pk_mul_f32 v[250:251], v[184:185], v[184:185]
	v_pk_fma_f32 v[182:183], v[216:217], v[216:217], v[182:183]
	v_pk_fma_f32 v[250:251], v[214:215], v[214:215], v[250:251]
	v_add_f32_e32 v182, v182, v183
	v_add_f32_e32 v232, v250, v251
	v_add_f32_e32 v232, v232, v182
	v_cvt_pk_bf16_f32 v182, v214, v215
	v_lshl_add_u64 v[214:215], s[26:27], 0, v[224:225]
	v_cvt_pk_bf16_f32 v183, v216, v217
	v_cvt_pk_bf16_f32 v184, v184, v185
	v_cvt_pk_bf16_f32 v185, v226, v227
	v_lshl_add_u64 v[214:215], v[202:203], 1, v[214:215]
	v_pk_fma_f32 v[216:217], v[194:195], v[116:117], v[180:181]
	v_pk_fma_f32 v[180:181], v[196:197], v[114:115], v[178:179]
	global_store_dwordx4 v[214:215], v[182:185], off
	v_pk_mul_f32 v[178:179], v[216:217], v[216:217]
	s_nop 0
	v_pk_fma_f32 v[182:183], v[194:195], v[120:121], v[220:221]
	v_pk_fma_f32 v[184:185], v[196:197], v[118:119], v[218:219]
	v_pk_mul_f32 v[218:219], v[180:181], v[180:181]
	v_pk_fma_f32 v[178:179], v[182:183], v[182:183], v[178:179]
	v_pk_fma_f32 v[218:219], v[184:185], v[184:185], v[218:219]
	v_add_f32_e32 v178, v178, v179
	v_add_f32_e32 v218, v218, v219
	v_add_f32_e32 v178, v218, v178
	v_add_f32_e32 v218, v232, v178
	v_cvt_pk_bf16_f32 v178, v184, v185
	v_cvt_pk_bf16_f32 v179, v182, v183
	v_cvt_pk_bf16_f32 v180, v180, v181
	v_cvt_pk_bf16_f32 v181, v216, v217
	global_store_dwordx4 v[214:215], v[178:181], off offset:256
	ds_bpermute_b32 v178, v248, v218
	s_waitcnt lgkmcnt(0)
	v_add_f32_e32 v178, v218, v178
	ds_bpermute_b32 v179, v249, v178
	s_and_saveexec_b64 s[34:35], s[6:7]
	s_cbranch_execz .LBB0_335
	v_lshlrev_b64 v[180:181], 6, v[204:205]
	v_lshl_add_u64 v[180:181], s[24:25], 0, v[180:181]
	v_lshl_add_u64 v[180:181], s[30:31], 2, v[180:181]
	s_lshl_b32 s84, s47, 2
	v_lshl_add_u64 v[180:181], v[180:181], 0, s[84:85]
	s_waitcnt lgkmcnt(0)
	v_add_f32_e32 v178, v178, v179
	global_store_dword v[180:181], v178, off

.LBB0_394:
	s_add_u32 s12, s10, 0xfffc0080
	s_addc_u32 s13, s11, -1
	s_add_u32 s48, s10, 0xfffc0000
	s_addc_u32 s49, s11, -1
	s_mov_b32 m0, s74
	ds_read_b128 v[50:53], v216
	ds_read_b128 v[54:57], v216 offset:1024
	ds_read_b128 v[58:61], v216 offset:2048
	ds_read_b128 v[62:65], v216 offset:3072
	ds_read_b128 v[162:165], v216 offset:16384
	ds_read_b128 v[166:169], v216 offset:17408
	ds_read_b128 v[170:173], v216 offset:18432
	ds_read_b128 v[174:177], v216 offset:19456
	ds_read_b128 v[178:181], v184
	ds_read_b128 v[186:189], v184 offset:1024
	ds_read_b128 v[192:195], v184 offset:2048
	ds_read_b128 v[196:199], v184 offset:3072
	ds_read_b128 v[200:203], v184 offset:4096
	ds_read_b128 v[204:207], v184 offset:5120
	ds_read_b128 v[208:211], v184 offset:6144
	ds_read_b128 v[212:215], v184 offset:7168
	global_load_lds_dwordx4 v150, s[48:49]
	s_add_i32 m0, s41, 0xc000
	s_nop 0
	global_load_lds_dwordx4 v158, s[10:11]
	s_add_i32 m0, s41, 0xe000
	s_cmp_eq_u32 s46, 12
	global_load_lds_dwordx4 v160, s[10:11]
	s_cselect_b32 s15, s31, s13
	s_cselect_b32 s14, s38, s12
	s_cselect_b32 s13, s29, s45
	s_cselect_b32 s12, s39, s44
	s_waitcnt vmcnt(8)
	s_waitcnt lgkmcnt(0)
	s_barrier
	s_setprio 1
	s_waitcnt lgkmcnt(0)
	v_mfma_f32_16x16x32_bf16 v[142:145], v[50:53], v[178:181], v[142:145]
	v_mfma_f32_16x16x32_bf16 v[138:141], v[58:61], v[178:181], v[138:141]
	v_mfma_f32_16x16x32_bf16 v[126:129], v[50:53], v[192:195], v[126:129]
	v_mfma_f32_16x16x32_bf16 v[122:125], v[58:61], v[192:195], v[122:125]
	v_mfma_f32_16x16x32_bf16 v[110:113], v[50:53], v[200:203], v[110:113]
	v_mfma_f32_16x16x32_bf16 v[106:109], v[58:61], v[200:203], v[106:109]
	v_mfma_f32_16x16x32_bf16 v[94:97], v[50:53], v[208:211], v[94:97]
	v_mfma_f32_16x16x32_bf16 v[90:93], v[58:61], v[208:211], v[90:93]
	v_mfma_f32_16x16x32_bf16 v[142:145], v[54:57], v[186:189], v[142:145]
	v_mfma_f32_16x16x32_bf16 v[138:141], v[62:65], v[186:189], v[138:141]
	v_mfma_f32_16x16x32_bf16 v[126:129], v[54:57], v[196:199], v[126:129]
	v_mfma_f32_16x16x32_bf16 v[122:125], v[62:65], v[196:199], v[122:125]
	v_mfma_f32_16x16x32_bf16 v[110:113], v[54:57], v[204:207], v[110:113]
	v_mfma_f32_16x16x32_bf16 v[106:109], v[62:65], v[204:207], v[106:109]
	v_mfma_f32_16x16x32_bf16 v[94:97], v[54:57], v[212:215], v[94:97]
	v_mfma_f32_16x16x32_bf16 v[90:93], v[62:65], v[212:215], v[90:93]
	s_setprio 0
	s_setprio 1
	v_mfma_f32_16x16x32_bf16 v[134:137], v[162:165], v[178:181], v[134:137]
	v_mfma_f32_16x16x32_bf16 v[130:133], v[170:173], v[178:181], v[130:133]
	v_mfma_f32_16x16x32_bf16 v[118:121], v[162:165], v[192:195], v[118:121]
	v_mfma_f32_16x16x32_bf16 v[114:117], v[170:173], v[192:195], v[114:117]
	v_mfma_f32_16x16x32_bf16 v[102:105], v[162:165], v[200:203], v[102:105]
	v_mfma_f32_16x16x32_bf16 v[98:101], v[170:173], v[200:203], v[98:101]
	v_mfma_f32_16x16x32_bf16 v[86:89], v[162:165], v[208:211], v[86:89]
	v_mfma_f32_16x16x32_bf16 v[82:85], v[170:173], v[208:211], v[82:85]
	v_mfma_f32_16x16x32_bf16 v[134:137], v[166:169], v[186:189], v[134:137]
	v_mfma_f32_16x16x32_bf16 v[130:133], v[174:177], v[186:189], v[130:133]
	v_mfma_f32_16x16x32_bf16 v[118:121], v[166:169], v[196:199], v[118:121]
	v_mfma_f32_16x16x32_bf16 v[114:117], v[174:177], v[196:199], v[114:117]
	v_mfma_f32_16x16x32_bf16 v[102:105], v[166:169], v[204:207], v[102:105]
	v_mfma_f32_16x16x32_bf16 v[98:101], v[174:177], v[204:207], v[98:101]
	v_mfma_f32_16x16x32_bf16 v[86:89], v[166:169], v[212:215], v[86:89]
	v_mfma_f32_16x16x32_bf16 v[82:85], v[174:177], v[212:215], v[82:85]
	s_setprio 0
	s_barrier
	s_add_i32 s47, s68, 0x10000
	s_mov_b32 m0, s47
	ds_read_b128 v[178:181], v184 offset:16384
	ds_read_b128 v[186:189], v184 offset:17408
	ds_read_b128 v[192:195], v184 offset:18432
	ds_read_b128 v[196:199], v184 offset:19456
	ds_read_b128 v[200:203], v184 offset:20480
	ds_read_b128 v[204:207], v184 offset:21504
	ds_read_b128 v[208:211], v184 offset:22528
	ds_read_b128 v[212:215], v184 offset:23552
	global_load_lds_dwordx4 v148, s[12:13]
	s_add_i32 m0, s47, 0x2000
	s_add_u32 s48, s12, 0x40000
	global_load_lds_dwordx4 v152, s[12:13]
	s_addc_u32 s49, s13, 0
	s_add_i32 s47, s68, 0x14000
	s_mov_b32 m0, s47
	s_nop 0
	global_load_lds_dwordx4 v148, s[48:49]
	s_add_i32 m0, s47, 0x2000
	s_nop 0
	global_load_lds_dwordx4 v152, s[48:49]
	s_mov_b32 m0, s41
	s_nop 0
	global_load_lds_dwordx4 v146, s[14:15]
	s_waitcnt vmcnt(7)
	s_waitcnt lgkmcnt(0)
	s_barrier
	s_setprio 1
	s_waitcnt lgkmcnt(0)
	v_mfma_f32_16x16x32_bf16 v[78:81], v[50:53], v[178:181], v[78:81]
	v_mfma_f32_16x16x32_bf16 v[74:77], v[58:61], v[178:181], v[74:77]
	v_mfma_f32_16x16x32_bf16 v[46:49], v[50:53], v[192:195], v[46:49]
	v_mfma_f32_16x16x32_bf16 v[42:45], v[58:61], v[192:195], v[42:45]
	v_mfma_f32_16x16x32_bf16 v[30:33], v[50:53], v[200:203], v[30:33]
	v_mfma_f32_16x16x32_bf16 v[26:29], v[58:61], v[200:203], v[26:29]
	v_mfma_f32_16x16x32_bf16 v[14:17], v[50:53], v[208:211], v[14:17]
	v_mfma_f32_16x16x32_bf16 v[10:13], v[58:61], v[208:211], v[10:13]
	v_mfma_f32_16x16x32_bf16 v[78:81], v[54:57], v[186:189], v[78:81]
	v_mfma_f32_16x16x32_bf16 v[74:77], v[62:65], v[186:189], v[74:77]
	v_mfma_f32_16x16x32_bf16 v[46:49], v[54:57], v[196:199], v[46:49]
	v_mfma_f32_16x16x32_bf16 v[42:45], v[62:65], v[196:199], v[42:45]
	v_mfma_f32_16x16x32_bf16 v[30:33], v[54:57], v[204:207], v[30:33]
	v_mfma_f32_16x16x32_bf16 v[26:29], v[62:65], v[204:207], v[26:29]
	v_mfma_f32_16x16x32_bf16 v[14:17], v[54:57], v[212:215], v[14:17]
	v_mfma_f32_16x16x32_bf16 v[10:13], v[62:65], v[212:215], v[10:13]
	s_setprio 0
	s_setprio 1
	v_mfma_f32_16x16x32_bf16 v[38:41], v[162:165], v[192:195], v[38:41]
	v_mfma_f32_16x16x32_bf16 v[34:37], v[170:173], v[192:195], v[34:37]
	v_mfma_f32_16x16x32_bf16 v[22:25], v[162:165], v[200:203], v[22:25]
	v_mfma_f32_16x16x32_bf16 v[18:21], v[170:173], v[200:203], v[18:21]
	v_mfma_f32_16x16x32_bf16 v[6:9], v[162:165], v[208:211], v[6:9]
	v_mfma_f32_16x16x32_bf16 v[2:5], v[170:173], v[208:211], v[2:5]
	v_mfma_f32_16x16x32_bf16 v[50:53], v[162:165], v[178:181], v[70:73]
	v_mfma_f32_16x16x32_bf16 v[54:57], v[170:173], v[178:181], v[66:69]
	v_mfma_f32_16x16x32_bf16 v[38:41], v[166:169], v[196:199], v[38:41]
	v_mfma_f32_16x16x32_bf16 v[34:37], v[174:177], v[196:199], v[34:37]
	v_mfma_f32_16x16x32_bf16 v[22:25], v[166:169], v[204:207], v[22:25]
	v_mfma_f32_16x16x32_bf16 v[18:21], v[174:177], v[204:207], v[18:21]
	v_mfma_f32_16x16x32_bf16 v[6:9], v[166:169], v[212:215], v[6:9]
	v_mfma_f32_16x16x32_bf16 v[2:5], v[174:177], v[212:215], v[2:5]
	v_mfma_f32_16x16x32_bf16 v[50:53], v[166:169], v[186:189], v[50:53]
	v_mfma_f32_16x16x32_bf16 v[54:57], v[174:177], v[186:189], v[54:57]
	s_setprio 0
	s_barrier
	s_mov_b32 m0, s43
	ds_read_b128 v[58:61], v216 offset:32768
	ds_read_b128 v[62:65], v216 offset:33792
	ds_read_b128 v[66:69], v216 offset:34816
	ds_read_b128 v[70:73], v216 offset:35840
	ds_read_b128 v[162:165], v216 offset:49152
	ds_read_b128 v[166:169], v216 offset:50176
	ds_read_b128 v[170:173], v216 offset:51200
	ds_read_b128 v[174:177], v216 offset:52224
	ds_read_b128 v[178:181], v184 offset:32768
	ds_read_b128 v[186:189], v184 offset:33792
	ds_read_b128 v[192:195], v184 offset:34816
	ds_read_b128 v[196:199], v184 offset:35840
	ds_read_b128 v[200:203], v184 offset:36864
	ds_read_b128 v[204:207], v184 offset:37888
	ds_read_b128 v[208:211], v184 offset:38912
	ds_read_b128 v[212:215], v184 offset:39936
	global_load_lds_dwordx4 v150, s[14:15]
	s_add_u32 s14, s14, 0x40000
	s_addc_u32 s15, s15, 0
	s_mov_b32 m0, s69
	s_nop 0
	global_load_lds_dwordx4 v146, s[14:15]
	s_mov_b32 m0, s70
	s_nop 0
	global_load_lds_dwordx4 v150, s[14:15]
	s_waitcnt vmcnt(8)
	s_waitcnt lgkmcnt(0)
	s_barrier
	s_setprio 1
	s_waitcnt lgkmcnt(0)
	v_mfma_f32_16x16x32_bf16 v[142:145], v[58:61], v[178:181], v[142:145]
	v_mfma_f32_16x16x32_bf16 v[138:141], v[66:69], v[178:181], v[138:141]
	v_mfma_f32_16x16x32_bf16 v[126:129], v[58:61], v[192:195], v[126:129]
	v_mfma_f32_16x16x32_bf16 v[122:125], v[66:69], v[192:195], v[122:125]
	v_mfma_f32_16x16x32_bf16 v[110:113], v[58:61], v[200:203], v[110:113]
	v_mfma_f32_16x16x32_bf16 v[106:109], v[66:69], v[200:203], v[106:109]
	v_mfma_f32_16x16x32_bf16 v[94:97], v[58:61], v[208:211], v[94:97]
	v_mfma_f32_16x16x32_bf16 v[90:93], v[66:69], v[208:211], v[90:93]
	v_mfma_f32_16x16x32_bf16 v[142:145], v[62:65], v[186:189], v[142:145]
	v_mfma_f32_16x16x32_bf16 v[138:141], v[70:73], v[186:189], v[138:141]
	v_mfma_f32_16x16x32_bf16 v[126:129], v[62:65], v[196:199], v[126:129]
	v_mfma_f32_16x16x32_bf16 v[122:125], v[70:73], v[196:199], v[122:125]
	v_mfma_f32_16x16x32_bf16 v[110:113], v[62:65], v[204:207], v[110:113]
	v_mfma_f32_16x16x32_bf16 v[106:109], v[70:73], v[204:207], v[106:109]
	v_mfma_f32_16x16x32_bf16 v[94:97], v[62:65], v[212:215], v[94:97]
	v_mfma_f32_16x16x32_bf16 v[90:93], v[70:73], v[212:215], v[90:93]
	s_setprio 0
	s_setprio 1
	v_mfma_f32_16x16x32_bf16 v[134:137], v[162:165], v[178:181], v[134:137]
	v_mfma_f32_16x16x32_bf16 v[130:133], v[170:173], v[178:181], v[130:133]
	v_mfma_f32_16x16x32_bf16 v[118:121], v[162:165], v[192:195], v[118:121]
	v_mfma_f32_16x16x32_bf16 v[114:117], v[170:173], v[192:195], v[114:117]
	v_mfma_f32_16x16x32_bf16 v[102:105], v[162:165], v[200:203], v[102:105]
	v_mfma_f32_16x16x32_bf16 v[98:101], v[170:173], v[200:203], v[98:101]
	v_mfma_f32_16x16x32_bf16 v[86:89], v[162:165], v[208:211], v[86:89]
	v_mfma_f32_16x16x32_bf16 v[82:85], v[170:173], v[208:211], v[82:85]
	v_mfma_f32_16x16x32_bf16 v[134:137], v[166:169], v[186:189], v[134:137]
	v_mfma_f32_16x16x32_bf16 v[130:133], v[174:177], v[186:189], v[130:133]
	v_mfma_f32_16x16x32_bf16 v[118:121], v[166:169], v[196:199], v[118:121]
	v_mfma_f32_16x16x32_bf16 v[114:117], v[174:177], v[196:199], v[114:117]
	v_mfma_f32_16x16x32_bf16 v[102:105], v[166:169], v[204:207], v[102:105]
	v_mfma_f32_16x16x32_bf16 v[98:101], v[174:177], v[204:207], v[98:101]
	v_mfma_f32_16x16x32_bf16 v[86:89], v[166:169], v[212:215], v[86:89]
	v_mfma_f32_16x16x32_bf16 v[82:85], v[174:177], v[212:215], v[82:85]
	s_setprio 0
	s_barrier
	s_add_u32 s12, s12, 0x80
	s_addc_u32 s13, s13, 0
	s_add_i32 s47, s68, 0x18000
	s_mov_b32 m0, s47
	ds_read_b128 v[178:181], v184 offset:49152
	ds_read_b128 v[186:189], v184 offset:50176
	ds_read_b128 v[192:195], v184 offset:51200
	ds_read_b128 v[196:199], v184 offset:52224
	ds_read_b128 v[200:203], v184 offset:53248
	ds_read_b128 v[204:207], v184 offset:54272
	ds_read_b128 v[208:211], v184 offset:55296
	ds_read_b128 v[212:215], v184 offset:56320
	global_load_lds_dwordx4 v148, s[12:13]
	s_add_i32 m0, s47, 0x2000
	s_add_u32 s48, s12, 0x40000
	global_load_lds_dwordx4 v152, s[12:13]
	s_addc_u32 s49, s13, 0
	s_add_i32 s47, s68, 0x1c000
	s_mov_b32 m0, s47
	s_add_u32 s14, s14, 0xfffc0080
	global_load_lds_dwordx4 v148, s[48:49]
	s_addc_u32 s15, s15, -1
	s_add_i32 m0, s47, 0x2000
	s_nop 0
	global_load_lds_dwordx4 v152, s[48:49]
	s_mov_b32 m0, s73
	s_nop 0
	global_load_lds_dwordx4 v146, s[14:15]
	s_waitcnt vmcnt(7)
	s_waitcnt lgkmcnt(0)
	s_barrier
	s_setprio 1
	s_waitcnt lgkmcnt(0)
	v_mfma_f32_16x16x32_bf16 v[78:81], v[58:61], v[178:181], v[78:81]
	v_mfma_f32_16x16x32_bf16 v[74:77], v[66:69], v[178:181], v[74:77]
	v_mfma_f32_16x16x32_bf16 v[46:49], v[58:61], v[192:195], v[46:49]
	v_mfma_f32_16x16x32_bf16 v[42:45], v[66:69], v[192:195], v[42:45]
	v_mfma_f32_16x16x32_bf16 v[30:33], v[58:61], v[200:203], v[30:33]
	v_mfma_f32_16x16x32_bf16 v[26:29], v[66:69], v[200:203], v[26:29]
	v_mfma_f32_16x16x32_bf16 v[14:17], v[58:61], v[208:211], v[14:17]
	v_mfma_f32_16x16x32_bf16 v[10:13], v[66:69], v[208:211], v[10:13]
	v_mfma_f32_16x16x32_bf16 v[78:81], v[62:65], v[186:189], v[78:81]
	v_mfma_f32_16x16x32_bf16 v[74:77], v[70:73], v[186:189], v[74:77]
	v_mfma_f32_16x16x32_bf16 v[46:49], v[62:65], v[196:199], v[46:49]
	v_mfma_f32_16x16x32_bf16 v[42:45], v[70:73], v[196:199], v[42:45]
	v_mfma_f32_16x16x32_bf16 v[30:33], v[62:65], v[204:207], v[30:33]
	v_mfma_f32_16x16x32_bf16 v[26:29], v[70:73], v[204:207], v[26:29]
	v_mfma_f32_16x16x32_bf16 v[14:17], v[62:65], v[212:215], v[14:17]
	v_mfma_f32_16x16x32_bf16 v[10:13], v[70:73], v[212:215], v[10:13]
	s_setprio 0
	s_setprio 1
	v_mfma_f32_16x16x32_bf16 v[50:53], v[162:165], v[178:181], v[50:53]
	v_mfma_f32_16x16x32_bf16 v[70:73], v[166:169], v[186:189], v[50:53]
	v_mfma_f32_16x16x32_bf16 v[50:53], v[170:173], v[178:181], v[54:57]
	v_mfma_f32_16x16x32_bf16 v[38:41], v[162:165], v[192:195], v[38:41]
	v_mfma_f32_16x16x32_bf16 v[34:37], v[170:173], v[192:195], v[34:37]
	v_mfma_f32_16x16x32_bf16 v[22:25], v[162:165], v[200:203], v[22:25]
	v_mfma_f32_16x16x32_bf16 v[18:21], v[170:173], v[200:203], v[18:21]
	v_mfma_f32_16x16x32_bf16 v[6:9], v[162:165], v[208:211], v[6:9]
	v_mfma_f32_16x16x32_bf16 v[2:5], v[170:173], v[208:211], v[2:5]
	v_mfma_f32_16x16x32_bf16 v[66:69], v[174:177], v[186:189], v[50:53]
	v_mfma_f32_16x16x32_bf16 v[38:41], v[166:169], v[196:199], v[38:41]
	v_mfma_f32_16x16x32_bf16 v[34:37], v[174:177], v[196:199], v[34:37]
	v_mfma_f32_16x16x32_bf16 v[22:25], v[166:169], v[204:207], v[22:25]
	v_mfma_f32_16x16x32_bf16 v[18:21], v[174:177], v[204:207], v[18:21]
	v_mfma_f32_16x16x32_bf16 v[6:9], v[166:169], v[212:215], v[6:9]
	v_mfma_f32_16x16x32_bf16 v[2:5], v[174:177], v[212:215], v[2:5]
	s_setprio 0
	s_barrier
	s_add_i32 s46, s46, 2
	s_add_u32 s10, s10, 0x100
	s_addc_u32 s11, s11, 0
	s_add_u32 s44, s44, 0x100
	s_addc_u32 s45, s45, 0
	s_cmp_gt_u32 s46, 13
	s_cbranch_scc0 .LBB0_394
	s_and_b64 vcc, exec, s[24:25]
	s_cbranch_vccz .LBB0_397
	s_barrier

.LBB0_458:
	s_add_i32 s69, s38, 2
	s_add_u32 s70, s36, 0x80
	s_addc_u32 s39, s37, 0
	s_mov_b32 m0, s55
	ds_read_b128 v[130:133], v202
	ds_read_b128 v[134:137], v202 offset:1024
	ds_read_b128 v[138:141], v202 offset:2048
	ds_read_b128 v[142:145], v202 offset:3072
	ds_read_b128 v[146:149], v202 offset:16384
	ds_read_b128 v[150:153], v202 offset:17408
	ds_read_b128 v[154:157], v202 offset:18432
	ds_read_b128 v[158:161], v202 offset:19456
	ds_read_b128 v[162:165], v209
	ds_read_b128 v[166:169], v209 offset:1024
	ds_read_b128 v[170:173], v209 offset:2048
	ds_read_b128 v[186:189], v209 offset:3072
	ds_read_b128 v[192:195], v209 offset:4096
	ds_read_b128 v[196:199], v209 offset:5120
	ds_read_b128 v[210:213], v209 offset:6144
	ds_read_b128 v[214:217], v209 offset:7168
	global_load_lds_dwordx4 v176, s[36:37]
	s_add_i32 m0, s23, 0xc000
	s_nop 0
	global_load_lds_dwordx4 v182, s[36:37]
	s_add_i32 m0, s23, 0xe000
	s_cmp_eq_u32 s63, s38
	global_load_lds_dwordx4 v184, s[36:37]
	s_cselect_b32 s39, s27, s39
	s_cselect_b32 s38, s35, s70
	s_cselect_b32 s71, s25, s68
	s_cselect_b32 s70, s66, s67
	s_waitcnt vmcnt(8)
	s_waitcnt lgkmcnt(0)
	s_barrier
	s_setprio 1
	s_waitcnt lgkmcnt(0)
	v_mfma_f32_16x16x32_bf16 v[126:129], v[130:133], v[162:165], v[126:129]
	v_mfma_f32_16x16x32_bf16 v[122:125], v[138:141], v[162:165], v[122:125]
	v_mfma_f32_16x16x32_bf16 v[118:121], v[130:133], v[170:173], v[118:121]
	v_mfma_f32_16x16x32_bf16 v[114:117], v[138:141], v[170:173], v[114:117]
	v_mfma_f32_16x16x32_bf16 v[110:113], v[130:133], v[192:195], v[110:113]
	v_mfma_f32_16x16x32_bf16 v[106:109], v[138:141], v[192:195], v[106:109]
	v_mfma_f32_16x16x32_bf16 v[102:105], v[130:133], v[210:213], v[102:105]
	v_mfma_f32_16x16x32_bf16 v[98:101], v[138:141], v[210:213], v[98:101]
	v_mfma_f32_16x16x32_bf16 v[126:129], v[134:137], v[166:169], v[126:129]
	v_mfma_f32_16x16x32_bf16 v[122:125], v[142:145], v[166:169], v[122:125]
	v_mfma_f32_16x16x32_bf16 v[118:121], v[134:137], v[186:189], v[118:121]
	v_mfma_f32_16x16x32_bf16 v[114:117], v[142:145], v[186:189], v[114:117]
	v_mfma_f32_16x16x32_bf16 v[110:113], v[134:137], v[196:199], v[110:113]
	v_mfma_f32_16x16x32_bf16 v[106:109], v[142:145], v[196:199], v[106:109]
	v_mfma_f32_16x16x32_bf16 v[102:105], v[134:137], v[214:217], v[102:105]
	v_mfma_f32_16x16x32_bf16 v[98:101], v[142:145], v[214:217], v[98:101]
	s_setprio 0
	s_setprio 1
	v_mfma_f32_16x16x32_bf16 v[82:85], v[146:149], v[162:165], v[82:85]
	v_mfma_f32_16x16x32_bf16 v[74:77], v[154:157], v[162:165], v[74:77]
	v_mfma_f32_16x16x32_bf16 v[70:73], v[146:149], v[170:173], v[70:73]
	v_mfma_f32_16x16x32_bf16 v[62:65], v[154:157], v[170:173], v[62:65]
	v_mfma_f32_16x16x32_bf16 v[54:57], v[146:149], v[192:195], v[54:57]
	v_mfma_f32_16x16x32_bf16 v[50:53], v[154:157], v[192:195], v[50:53]
	v_mfma_f32_16x16x32_bf16 v[38:41], v[146:149], v[210:213], v[38:41]
	v_mfma_f32_16x16x32_bf16 v[34:37], v[154:157], v[210:213], v[34:37]
	v_mfma_f32_16x16x32_bf16 v[82:85], v[150:153], v[166:169], v[82:85]
	v_mfma_f32_16x16x32_bf16 v[74:77], v[158:161], v[166:169], v[74:77]
	v_mfma_f32_16x16x32_bf16 v[70:73], v[150:153], v[186:189], v[70:73]
	v_mfma_f32_16x16x32_bf16 v[62:65], v[158:161], v[186:189], v[62:65]
	v_mfma_f32_16x16x32_bf16 v[54:57], v[150:153], v[196:199], v[54:57]
	v_mfma_f32_16x16x32_bf16 v[50:53], v[158:161], v[196:199], v[50:53]
	v_mfma_f32_16x16x32_bf16 v[38:41], v[150:153], v[214:217], v[38:41]
	v_mfma_f32_16x16x32_bf16 v[34:37], v[158:161], v[214:217], v[34:37]
	s_setprio 0
	s_barrier
	s_add_i32 s72, s45, 0x10000
	s_mov_b32 m0, s72
	ds_read_b128 v[162:165], v209 offset:16384
	ds_read_b128 v[166:169], v209 offset:17408
	ds_read_b128 v[170:173], v209 offset:18432
	ds_read_b128 v[186:189], v209 offset:19456
	ds_read_b128 v[192:195], v209 offset:20480
	ds_read_b128 v[196:199], v209 offset:21504
	ds_read_b128 v[210:213], v209 offset:22528
	ds_read_b128 v[214:217], v209 offset:23552
	global_load_lds_dwordx4 v0, s[70:71]
	s_add_i32 m0, s72, 0x2000
	s_add_i32 s72, s45, 0x14000
	global_load_lds_dwordx4 v174, s[70:71]
	s_add_u32 s70, s70, s84
	s_addc_u32 s71, s71, 0
	s_mov_b32 m0, s72
	s_nop 0
	global_load_lds_dwordx4 v0, s[70:71]
	s_add_i32 m0, s72, 0x2000
	s_nop 0
	global_load_lds_dwordx4 v174, s[70:71]
	s_mov_b32 m0, s23
	s_nop 0
	global_load_lds_dwordx4 v178, s[38:39]
	s_waitcnt vmcnt(7)
	s_waitcnt lgkmcnt(0)
	s_barrier
	s_setprio 1
	s_waitcnt lgkmcnt(0)
	v_mfma_f32_16x16x32_bf16 v[94:97], v[130:133], v[162:165], v[94:97]
	v_mfma_f32_16x16x32_bf16 v[90:93], v[138:141], v[162:165], v[90:93]
	v_mfma_f32_16x16x32_bf16 v[86:89], v[130:133], v[170:173], v[86:89]
	v_mfma_f32_16x16x32_bf16 v[78:81], v[138:141], v[170:173], v[78:81]
	v_mfma_f32_16x16x32_bf16 v[66:69], v[130:133], v[192:195], v[66:69]
	v_mfma_f32_16x16x32_bf16 v[58:61], v[138:141], v[192:195], v[58:61]
	v_mfma_f32_16x16x32_bf16 v[46:49], v[130:133], v[210:213], v[46:49]
	v_mfma_f32_16x16x32_bf16 v[42:45], v[138:141], v[210:213], v[42:45]
	v_mfma_f32_16x16x32_bf16 v[94:97], v[134:137], v[166:169], v[94:97]
	v_mfma_f32_16x16x32_bf16 v[90:93], v[142:145], v[166:169], v[90:93]
	v_mfma_f32_16x16x32_bf16 v[86:89], v[134:137], v[186:189], v[86:89]
	v_mfma_f32_16x16x32_bf16 v[78:81], v[142:145], v[186:189], v[78:81]
	v_mfma_f32_16x16x32_bf16 v[66:69], v[134:137], v[196:199], v[66:69]
	v_mfma_f32_16x16x32_bf16 v[58:61], v[142:145], v[196:199], v[58:61]
	v_mfma_f32_16x16x32_bf16 v[46:49], v[134:137], v[214:217], v[46:49]
	v_mfma_f32_16x16x32_bf16 v[42:45], v[142:145], v[214:217], v[42:45]
	s_setprio 0
	s_setprio 1
	v_mfma_f32_16x16x32_bf16 v[30:33], v[146:149], v[162:165], v[30:33]
	v_mfma_f32_16x16x32_bf16 v[26:29], v[154:157], v[162:165], v[26:29]
	v_mfma_f32_16x16x32_bf16 v[22:25], v[146:149], v[170:173], v[22:25]
	v_mfma_f32_16x16x32_bf16 v[18:21], v[154:157], v[170:173], v[18:21]
	v_mfma_f32_16x16x32_bf16 v[14:17], v[146:149], v[192:195], v[14:17]
	v_mfma_f32_16x16x32_bf16 v[10:13], v[154:157], v[192:195], v[10:13]
	v_mfma_f32_16x16x32_bf16 v[6:9], v[146:149], v[210:213], v[6:9]
	v_mfma_f32_16x16x32_bf16 v[2:5], v[154:157], v[210:213], v[2:5]
	v_mfma_f32_16x16x32_bf16 v[30:33], v[150:153], v[166:169], v[30:33]
	v_mfma_f32_16x16x32_bf16 v[26:29], v[158:161], v[166:169], v[26:29]
	v_mfma_f32_16x16x32_bf16 v[22:25], v[150:153], v[186:189], v[22:25]
	v_mfma_f32_16x16x32_bf16 v[18:21], v[158:161], v[186:189], v[18:21]
	v_mfma_f32_16x16x32_bf16 v[14:17], v[150:153], v[196:199], v[14:17]
	v_mfma_f32_16x16x32_bf16 v[10:13], v[158:161], v[196:199], v[10:13]
	v_mfma_f32_16x16x32_bf16 v[6:9], v[150:153], v[214:217], v[6:9]
	v_mfma_f32_16x16x32_bf16 v[2:5], v[158:161], v[214:217], v[2:5]
	s_setprio 0
	s_barrier
	s_mov_b32 m0, s51
	ds_read_b128 v[130:133], v202 offset:32768
	ds_read_b128 v[134:137], v202 offset:33792
	ds_read_b128 v[138:141], v202 offset:34816
	ds_read_b128 v[142:145], v202 offset:35840
	ds_read_b128 v[146:149], v202 offset:49152
	ds_read_b128 v[150:153], v202 offset:50176
	ds_read_b128 v[154:157], v202 offset:51200
	ds_read_b128 v[158:161], v202 offset:52224
	ds_read_b128 v[162:165], v209 offset:32768
	ds_read_b128 v[166:169], v209 offset:33792
	ds_read_b128 v[170:173], v209 offset:34816
	ds_read_b128 v[186:189], v209 offset:35840
	ds_read_b128 v[192:195], v209 offset:36864
	ds_read_b128 v[196:199], v209 offset:37888
	ds_read_b128 v[210:213], v209 offset:38912
	ds_read_b128 v[214:217], v209 offset:39936
	global_load_lds_dwordx4 v176, s[38:39]
	s_add_u32 s38, s38, s84
	s_addc_u32 s39, s39, 0
	s_mov_b32 m0, s52
	s_nop 0
	global_load_lds_dwordx4 v178, s[38:39]
	s_mov_b32 m0, s53
	s_nop 0
	global_load_lds_dwordx4 v176, s[38:39]
	s_waitcnt vmcnt(8)
	s_waitcnt lgkmcnt(0)
	s_barrier
	s_setprio 1
	s_waitcnt lgkmcnt(0)
	v_mfma_f32_16x16x32_bf16 v[126:129], v[130:133], v[162:165], v[126:129]
	v_mfma_f32_16x16x32_bf16 v[122:125], v[138:141], v[162:165], v[122:125]
	v_mfma_f32_16x16x32_bf16 v[118:121], v[130:133], v[170:173], v[118:121]
	v_mfma_f32_16x16x32_bf16 v[114:117], v[138:141], v[170:173], v[114:117]
	v_mfma_f32_16x16x32_bf16 v[110:113], v[130:133], v[192:195], v[110:113]
	v_mfma_f32_16x16x32_bf16 v[106:109], v[138:141], v[192:195], v[106:109]
	v_mfma_f32_16x16x32_bf16 v[102:105], v[130:133], v[210:213], v[102:105]
	v_mfma_f32_16x16x32_bf16 v[98:101], v[138:141], v[210:213], v[98:101]
	v_mfma_f32_16x16x32_bf16 v[126:129], v[134:137], v[166:169], v[126:129]
	v_mfma_f32_16x16x32_bf16 v[122:125], v[142:145], v[166:169], v[122:125]
	v_mfma_f32_16x16x32_bf16 v[118:121], v[134:137], v[186:189], v[118:121]
	v_mfma_f32_16x16x32_bf16 v[114:117], v[142:145], v[186:189], v[114:117]
	v_mfma_f32_16x16x32_bf16 v[110:113], v[134:137], v[196:199], v[110:113]
	v_mfma_f32_16x16x32_bf16 v[106:109], v[142:145], v[196:199], v[106:109]
	v_mfma_f32_16x16x32_bf16 v[102:105], v[134:137], v[214:217], v[102:105]
	v_mfma_f32_16x16x32_bf16 v[98:101], v[142:145], v[214:217], v[98:101]
	s_setprio 0
	s_setprio 1
	v_mfma_f32_16x16x32_bf16 v[82:85], v[146:149], v[162:165], v[82:85]
	v_mfma_f32_16x16x32_bf16 v[74:77], v[154:157], v[162:165], v[74:77]
	v_mfma_f32_16x16x32_bf16 v[70:73], v[146:149], v[170:173], v[70:73]
	v_mfma_f32_16x16x32_bf16 v[62:65], v[154:157], v[170:173], v[62:65]
	v_mfma_f32_16x16x32_bf16 v[54:57], v[146:149], v[192:195], v[54:57]
	v_mfma_f32_16x16x32_bf16 v[50:53], v[154:157], v[192:195], v[50:53]
	v_mfma_f32_16x16x32_bf16 v[38:41], v[146:149], v[210:213], v[38:41]
	v_mfma_f32_16x16x32_bf16 v[34:37], v[154:157], v[210:213], v[34:37]
	v_mfma_f32_16x16x32_bf16 v[82:85], v[150:153], v[166:169], v[82:85]
	v_mfma_f32_16x16x32_bf16 v[74:77], v[158:161], v[166:169], v[74:77]
	v_mfma_f32_16x16x32_bf16 v[70:73], v[150:153], v[186:189], v[70:73]
	v_mfma_f32_16x16x32_bf16 v[62:65], v[158:161], v[186:189], v[62:65]
	v_mfma_f32_16x16x32_bf16 v[54:57], v[150:153], v[196:199], v[54:57]
	v_mfma_f32_16x16x32_bf16 v[50:53], v[158:161], v[196:199], v[50:53]
	v_mfma_f32_16x16x32_bf16 v[38:41], v[150:153], v[214:217], v[38:41]
	v_mfma_f32_16x16x32_bf16 v[34:37], v[158:161], v[214:217], v[34:37]
	s_setprio 0
	s_barrier
	s_add_u32 s70, s70, 0x80
	s_addc_u32 s71, s71, 0
	s_add_i32 s72, s45, 0x1c000
	s_mov_b32 m0, s72
	ds_read_b128 v[162:165], v209 offset:49152
	ds_read_b128 v[166:169], v209 offset:50176
	ds_read_b128 v[170:173], v209 offset:51200
	ds_read_b128 v[186:189], v209 offset:52224
	ds_read_b128 v[192:195], v209 offset:53248
	ds_read_b128 v[196:199], v209 offset:54272
	ds_read_b128 v[210:213], v209 offset:55296
	ds_read_b128 v[214:217], v209 offset:56320
	global_load_lds_dwordx4 v0, s[70:71]
	s_add_i32 m0, s72, 0x2000
	s_add_i32 s72, s45, 0x18000
	global_load_lds_dwordx4 v174, s[70:71]
	s_sub_u32 s70, s70, s84
	s_subb_u32 s71, s71, 0
	s_mov_b32 m0, s72
	s_sub_u32 s38, s38, s84
	global_load_lds_dwordx4 v0, s[70:71]
	s_subb_u32 s39, s39, 0
	s_add_i32 m0, s72, 0x2000
	s_add_u32 s38, s38, 0x80
	global_load_lds_dwordx4 v174, s[70:71]
	s_addc_u32 s39, s39, 0
	s_mov_b32 m0, s54
	s_nop 0
	global_load_lds_dwordx4 v178, s[38:39]
	s_waitcnt vmcnt(7)
	s_waitcnt lgkmcnt(0)
	s_barrier
	s_setprio 1
	s_waitcnt lgkmcnt(0)
	v_mfma_f32_16x16x32_bf16 v[94:97], v[130:133], v[162:165], v[94:97]
	v_mfma_f32_16x16x32_bf16 v[90:93], v[138:141], v[162:165], v[90:93]
	v_mfma_f32_16x16x32_bf16 v[86:89], v[130:133], v[170:173], v[86:89]
	v_mfma_f32_16x16x32_bf16 v[78:81], v[138:141], v[170:173], v[78:81]
	v_mfma_f32_16x16x32_bf16 v[66:69], v[130:133], v[192:195], v[66:69]
	v_mfma_f32_16x16x32_bf16 v[58:61], v[138:141], v[192:195], v[58:61]
	v_mfma_f32_16x16x32_bf16 v[46:49], v[130:133], v[210:213], v[46:49]
	v_mfma_f32_16x16x32_bf16 v[42:45], v[138:141], v[210:213], v[42:45]
	v_mfma_f32_16x16x32_bf16 v[94:97], v[134:137], v[166:169], v[94:97]
	v_mfma_f32_16x16x32_bf16 v[90:93], v[142:145], v[166:169], v[90:93]
	v_mfma_f32_16x16x32_bf16 v[86:89], v[134:137], v[186:189], v[86:89]
	v_mfma_f32_16x16x32_bf16 v[78:81], v[142:145], v[186:189], v[78:81]
	v_mfma_f32_16x16x32_bf16 v[66:69], v[134:137], v[196:199], v[66:69]
	v_mfma_f32_16x16x32_bf16 v[58:61], v[142:145], v[196:199], v[58:61]
	v_mfma_f32_16x16x32_bf16 v[46:49], v[134:137], v[214:217], v[46:49]
	v_mfma_f32_16x16x32_bf16 v[42:45], v[142:145], v[214:217], v[42:45]
	s_setprio 0
	s_setprio 1
	v_mfma_f32_16x16x32_bf16 v[30:33], v[146:149], v[162:165], v[30:33]
	v_mfma_f32_16x16x32_bf16 v[26:29], v[154:157], v[162:165], v[26:29]
	v_mfma_f32_16x16x32_bf16 v[22:25], v[146:149], v[170:173], v[22:25]
	v_mfma_f32_16x16x32_bf16 v[18:21], v[154:157], v[170:173], v[18:21]
	v_mfma_f32_16x16x32_bf16 v[14:17], v[146:149], v[192:195], v[14:17]
	v_mfma_f32_16x16x32_bf16 v[10:13], v[154:157], v[192:195], v[10:13]
	v_mfma_f32_16x16x32_bf16 v[6:9], v[146:149], v[210:213], v[6:9]
	v_mfma_f32_16x16x32_bf16 v[2:5], v[154:157], v[210:213], v[2:5]
	v_mfma_f32_16x16x32_bf16 v[30:33], v[150:153], v[166:169], v[30:33]
	v_mfma_f32_16x16x32_bf16 v[26:29], v[158:161], v[166:169], v[26:29]
	v_mfma_f32_16x16x32_bf16 v[22:25], v[150:153], v[186:189], v[22:25]
	v_mfma_f32_16x16x32_bf16 v[18:21], v[158:161], v[186:189], v[18:21]
	v_mfma_f32_16x16x32_bf16 v[14:17], v[150:153], v[196:199], v[14:17]
	v_mfma_f32_16x16x32_bf16 v[10:13], v[158:161], v[196:199], v[10:13]
	v_mfma_f32_16x16x32_bf16 v[6:9], v[150:153], v[214:217], v[6:9]
	v_mfma_f32_16x16x32_bf16 v[2:5], v[158:161], v[214:217], v[2:5]
	s_setprio 0
	s_barrier
	s_add_u32 s36, s36, 0x100
	s_addc_u32 s37, s37, 0
	s_add_u32 s67, s67, 0x100
	s_addc_u32 s68, s68, 0
	s_cmp_ge_u32 s69, s59
	s_mov_b32 s38, s69
	s_cbranch_scc0 .LBB0_458
	s_and_b64 vcc, exec, s[18:19]
	s_cbranch_vccz .LBB0_461
	s_barrier
